# p3b epilogue: per-chunk store waits dropped; p3c-L0 epi: x loads of 4 chunks issued up front, store waits dropped
# speedup vs baseline: 1.1022x; 1.0127x over previous
.LBB0_1743:
	s_add_i32 s26, s26, 1
	s_add_u32 s48, s48, 0x100000
	s_addc_u32 s49, s49, 0
	v_lshlrev_b32_e32 v14, 16, v8
	v_and_b32_e32 v15, 0xffff0000, v8
	s_waitcnt lgkmcnt(0)
	v_lshlrev_b32_e32 v16, 16, v4
	v_and_b32_e32 v17, 0xffff0000, v4
	v_lshlrev_b32_e32 v18, 16, v0
	v_and_b32_e32 v19, 0xffff0000, v0
	s_add_u32 s46, s46, 0x100000
	v_pk_fma_f32 v[14:15], v[14:15], v[16:17], v[18:19]
	s_addc_u32 s47, s47, 0
	v_cvt_pk_bf16_f32 v0, v14, v15
	v_lshlrev_b32_e32 v8, 16, v9
	v_and_b32_e32 v9, 0xffff0000, v9
	v_lshlrev_b32_e32 v4, 16, v5
	v_and_b32_e32 v5, 0xffff0000, v5
	v_lshlrev_b32_e32 v14, 16, v1
	v_and_b32_e32 v15, 0xffff0000, v1
	s_add_u32 s44, s44, 0x100000
	v_pk_fma_f32 v[4:5], v[8:9], v[4:5], v[14:15]
	s_addc_u32 s45, s45, 0
	v_cvt_pk_bf16_f32 v1, v4, v5
	v_lshlrev_b32_e32 v4, 16, v10
	v_and_b32_e32 v5, 0xffff0000, v10
	v_lshlrev_b32_e32 v8, 16, v6
	v_and_b32_e32 v9, 0xffff0000, v6
	v_lshlrev_b32_e32 v14, 16, v2
	v_and_b32_e32 v15, 0xffff0000, v2
	s_add_u32 s40, s40, 0x100000
	v_pk_fma_f32 v[4:5], v[4:5], v[8:9], v[14:15]
	s_addc_u32 s41, s41, 0
	v_cvt_pk_bf16_f32 v2, v4, v5
	v_lshlrev_b32_e32 v4, 16, v11
	v_and_b32_e32 v5, 0xffff0000, v11
	v_lshlrev_b32_e32 v6, 16, v7
	v_and_b32_e32 v7, 0xffff0000, v7
	v_lshlrev_b32_e32 v8, 16, v3
	v_and_b32_e32 v9, 0xffff0000, v3
	s_add_u32 s34, s34, 0x100000
	v_pk_fma_f32 v[4:5], v[4:5], v[6:7], v[8:9]
	s_addc_u32 s35, s35, 0
	v_cvt_pk_bf16_f32 v3, v4, v5
	s_cmp_lg_u32 s26, s68
	global_store_dwordx4 v[12:13], v[0:3], off
	s_cbranch_scc0 .LBB0_1740

.LBB0_1750:
	v_lshlrev_b32_e32 v16, 16, v8
	v_and_b32_e32 v17, 0xffff0000, v8
	s_waitcnt lgkmcnt(0)
	v_lshlrev_b32_e32 v18, 16, v4
	v_and_b32_e32 v19, 0xffff0000, v4
	v_lshlrev_b32_e32 v20, 16, v0
	v_and_b32_e32 v21, 0xffff0000, v0
	v_pk_fma_f32 v[16:17], v[16:17], v[18:19], v[20:21]
	v_lshlrev_b32_e32 v8, 16, v9
	v_cvt_pk_bf16_f32 v0, v16, v17
	v_and_b32_e32 v9, 0xffff0000, v9
	v_lshlrev_b32_e32 v4, 16, v5
	v_and_b32_e32 v5, 0xffff0000, v5
	v_lshlrev_b32_e32 v16, 16, v1
	v_and_b32_e32 v17, 0xffff0000, v1
	v_pk_fma_f32 v[4:5], v[8:9], v[4:5], v[16:17]
	v_lshlrev_b32_e32 v8, 16, v6
	v_cvt_pk_bf16_f32 v1, v4, v5
	v_lshlrev_b32_e32 v4, 16, v10
	v_and_b32_e32 v5, 0xffff0000, v10
	v_and_b32_e32 v9, 0xffff0000, v6
	v_lshlrev_b32_e32 v16, 16, v2
	v_and_b32_e32 v17, 0xffff0000, v2
	v_pk_fma_f32 v[4:5], v[4:5], v[8:9], v[16:17]
	v_lshlrev_b32_e32 v6, 16, v7
	v_cvt_pk_bf16_f32 v2, v4, v5
	v_lshlrev_b32_e32 v4, 16, v11
	v_and_b32_e32 v5, 0xffff0000, v11
	v_and_b32_e32 v7, 0xffff0000, v7
	v_lshlrev_b32_e32 v8, 16, v3
	v_and_b32_e32 v9, 0xffff0000, v3
	v_pk_fma_f32 v[4:5], v[4:5], v[6:7], v[8:9]
	s_and_b64 vcc, exec, s[0:1]
	v_cvt_pk_bf16_f32 v3, v4, v5
	global_store_dwordx4 v[12:13], v[0:3], off
	v_mov_b32_e32 v10, 0
	v_mov_b32_e32 v11, 0
	v_add_u32_e32 v0, 0x200, v15
	v_ashrrev_i32_e32 v1, 4, v0
	v_add_u32_e32 v0, s69, v1
	v_mov_b64_e32 v[2:3], s[4:5]
	v_mad_i64_i32 v[2:3], s[50:51], v0, s66, v[2:3]
	v_lshl_add_u64 v[2:3], s[16:17], 1, v[2:3]
	v_lshl_add_u64 v[2:3], s[22:23], 1, v[2:3]
	v_lshl_add_u64 v[2:3], v[2:3], 0, v[128:129]
	v_mov_b64_e32 v[6:7], v[28:29]
	v_mov_b64_e32 v[8:9], v[30:31]
	v_mad_u64_u32 v[2:3], s[50:51], v1, s60, v[14:15]
	ds_read_b128 v[2:5], v2
	v_ashrrev_i32_e32 v1, 31, v0
	v_lshlrev_b64 v[0:1], 11, v[0:1]
	v_lshl_add_u64 v[0:1], s[24:25], 0, v[0:1]
	v_lshl_add_u64 v[16:17], v[0:1], 0, v[128:129]
	v_mov_b32_e32 v0, 0
	v_mov_b32_e32 v12, 0
	v_mov_b32_e32 v13, 0
	s_cbranch_vccnz .LBB0_1752
	v_mov_b64_e32 v[10:11], v[56:57]
	v_mov_b64_e32 v[12:13], v[58:59]
.LBB0_1752:
	v_lshlrev_b32_e32 v18, 16, v6
	v_and_b32_e32 v19, 0xffff0000, v6
	s_waitcnt lgkmcnt(0)
	v_lshlrev_b32_e32 v20, 16, v2
	v_and_b32_e32 v21, 0xffff0000, v2
	v_lshlrev_b32_e32 v22, 16, v10
	v_and_b32_e32 v23, 0xffff0000, v10
	v_pk_fma_f32 v[18:19], v[18:19], v[20:21], v[22:23]
	v_lshlrev_b32_e32 v6, 16, v7
	v_cvt_pk_bf16_f32 v2, v18, v19
	v_and_b32_e32 v7, 0xffff0000, v7
	v_lshlrev_b32_e32 v18, 16, v3
	v_and_b32_e32 v19, 0xffff0000, v3
	v_lshlrev_b32_e32 v10, 16, v11
	v_and_b32_e32 v11, 0xffff0000, v11
	v_pk_fma_f32 v[6:7], v[6:7], v[18:19], v[10:11]
	v_lshlrev_b32_e32 v10, 16, v4
	v_cvt_pk_bf16_f32 v3, v6, v7
	v_lshlrev_b32_e32 v6, 16, v8
	v_and_b32_e32 v7, 0xffff0000, v8
	v_and_b32_e32 v11, 0xffff0000, v4
	v_lshlrev_b32_e32 v18, 16, v12
	v_and_b32_e32 v19, 0xffff0000, v12
	v_pk_fma_f32 v[6:7], v[6:7], v[10:11], v[18:19]
	v_lshlrev_b32_e32 v8, 16, v5
	v_cvt_pk_bf16_f32 v4, v6, v7
	v_lshlrev_b32_e32 v6, 16, v9
	v_and_b32_e32 v7, 0xffff0000, v9
	v_and_b32_e32 v9, 0xffff0000, v5
	v_lshlrev_b32_e32 v10, 16, v13
	v_and_b32_e32 v11, 0xffff0000, v13
	v_pk_fma_f32 v[6:7], v[6:7], v[8:9], v[10:11]
	v_add_u32_e32 v1, 0x300, v15
	v_cvt_pk_bf16_f32 v5, v6, v7
	v_ashrrev_i32_e32 v1, 4, v1
	global_store_dwordx4 v[16:17], v[2:5], off
	s_and_b64 vcc, exec, s[0:1]
	s_nop 0
	v_add_u32_e32 v2, s69, v1
	v_mov_b64_e32 v[4:5], s[4:5]
	v_mad_i64_i32 v[4:5], s[50:51], v2, s66, v[4:5]
	v_lshl_add_u64 v[4:5], s[16:17], 1, v[4:5]
	v_lshl_add_u64 v[4:5], s[22:23], 1, v[4:5]
	v_lshl_add_u64 v[4:5], v[4:5], 0, v[128:129]
	v_mov_b64_e32 v[8:9], v[32:33]
	v_mov_b64_e32 v[10:11], v[34:35]
	v_mad_u64_u32 v[4:5], s[50:51], v1, s60, v[14:15]
	ds_read_b128 v[4:7], v4
	v_ashrrev_i32_e32 v3, 31, v2
	v_lshlrev_b64 v[2:3], 11, v[2:3]
	v_lshl_add_u64 v[2:3], s[24:25], 0, v[2:3]
	v_lshl_add_u64 v[12:13], v[2:3], 0, v[128:129]
	v_mov_b32_e32 v1, 0
	v_mov_b32_e32 v2, 0
	v_mov_b32_e32 v3, 0
	s_cbranch_vccnz .LBB0_1754
	v_mov_b64_e32 v[0:1], v[60:61]
	v_mov_b64_e32 v[2:3], v[62:63]
.LBB0_1754:
	v_lshlrev_b32_e32 v16, 16, v8
	v_and_b32_e32 v17, 0xffff0000, v8
	s_waitcnt lgkmcnt(0)
	v_lshlrev_b32_e32 v18, 16, v4
	v_and_b32_e32 v19, 0xffff0000, v4
	v_lshlrev_b32_e32 v20, 16, v0
	v_and_b32_e32 v21, 0xffff0000, v0
	v_pk_fma_f32 v[16:17], v[16:17], v[18:19], v[20:21]
	v_lshlrev_b32_e32 v8, 16, v9
	v_cvt_pk_bf16_f32 v0, v16, v17
	v_and_b32_e32 v9, 0xffff0000, v9
	v_lshlrev_b32_e32 v4, 16, v5
	v_and_b32_e32 v5, 0xffff0000, v5
	v_lshlrev_b32_e32 v16, 16, v1
	v_and_b32_e32 v17, 0xffff0000, v1
	v_pk_fma_f32 v[4:5], v[8:9], v[4:5], v[16:17]
	v_lshlrev_b32_e32 v8, 16, v6
	v_cvt_pk_bf16_f32 v1, v4, v5
	v_lshlrev_b32_e32 v4, 16, v10
	v_and_b32_e32 v5, 0xffff0000, v10
	v_and_b32_e32 v9, 0xffff0000, v6
	v_lshlrev_b32_e32 v16, 16, v2
	v_and_b32_e32 v17, 0xffff0000, v2
	v_pk_fma_f32 v[4:5], v[4:5], v[8:9], v[16:17]
	v_lshlrev_b32_e32 v6, 16, v7
	v_cvt_pk_bf16_f32 v2, v4, v5
	v_lshlrev_b32_e32 v4, 16, v11
	v_and_b32_e32 v5, 0xffff0000, v11
	v_and_b32_e32 v7, 0xffff0000, v7
	v_lshlrev_b32_e32 v8, 16, v3
	v_and_b32_e32 v9, 0xffff0000, v3
	v_pk_fma_f32 v[4:5], v[4:5], v[6:7], v[8:9]
	s_and_b64 vcc, exec, s[0:1]
	v_cvt_pk_bf16_f32 v3, v4, v5
	global_store_dwordx4 v[12:13], v[0:3], off
	v_mov_b32_e32 v10, 0
	v_mov_b32_e32 v11, 0
	v_add_u32_e32 v0, 0x400, v15
	v_ashrrev_i32_e32 v1, 4, v0
	v_add_u32_e32 v0, s69, v1
	v_mov_b64_e32 v[2:3], s[4:5]
	v_mad_i64_i32 v[2:3], s[50:51], v0, s66, v[2:3]
	v_lshl_add_u64 v[2:3], s[16:17], 1, v[2:3]
	v_lshl_add_u64 v[2:3], s[22:23], 1, v[2:3]
	v_lshl_add_u64 v[2:3], v[2:3], 0, v[128:129]
	v_mov_b64_e32 v[6:7], v[36:37]
	v_mov_b64_e32 v[8:9], v[38:39]
	v_mad_u64_u32 v[2:3], s[50:51], v1, s60, v[14:15]
	ds_read_b128 v[2:5], v2
	v_ashrrev_i32_e32 v1, 31, v0
	v_lshlrev_b64 v[0:1], 11, v[0:1]
	v_lshl_add_u64 v[0:1], s[24:25], 0, v[0:1]
	v_lshl_add_u64 v[16:17], v[0:1], 0, v[128:129]
	v_mov_b32_e32 v0, 0
	v_mov_b32_e32 v12, 0
	v_mov_b32_e32 v13, 0
	s_cbranch_vccnz .LBB0_1756
	v_mov_b64_e32 v[10:11], v[64:65]
	v_mov_b64_e32 v[12:13], v[66:67]
.LBB0_1756:
	v_lshlrev_b32_e32 v18, 16, v6
	v_and_b32_e32 v19, 0xffff0000, v6
	s_waitcnt lgkmcnt(0)
	v_lshlrev_b32_e32 v20, 16, v2
	v_and_b32_e32 v21, 0xffff0000, v2
	v_lshlrev_b32_e32 v22, 16, v10
	v_and_b32_e32 v23, 0xffff0000, v10
	v_pk_fma_f32 v[18:19], v[18:19], v[20:21], v[22:23]
	v_lshlrev_b32_e32 v6, 16, v7
	v_cvt_pk_bf16_f32 v2, v18, v19
	v_and_b32_e32 v7, 0xffff0000, v7
	v_lshlrev_b32_e32 v18, 16, v3
	v_and_b32_e32 v19, 0xffff0000, v3
	v_lshlrev_b32_e32 v10, 16, v11
	v_and_b32_e32 v11, 0xffff0000, v11
	v_pk_fma_f32 v[6:7], v[6:7], v[18:19], v[10:11]
	v_lshlrev_b32_e32 v10, 16, v4
	v_cvt_pk_bf16_f32 v3, v6, v7
	v_lshlrev_b32_e32 v6, 16, v8
	v_and_b32_e32 v7, 0xffff0000, v8
	v_and_b32_e32 v11, 0xffff0000, v4
	v_lshlrev_b32_e32 v18, 16, v12
	v_and_b32_e32 v19, 0xffff0000, v12
	v_pk_fma_f32 v[6:7], v[6:7], v[10:11], v[18:19]
	v_lshlrev_b32_e32 v8, 16, v5
	v_cvt_pk_bf16_f32 v4, v6, v7
	v_lshlrev_b32_e32 v6, 16, v9
	v_and_b32_e32 v7, 0xffff0000, v9
	v_and_b32_e32 v9, 0xffff0000, v5
	v_lshlrev_b32_e32 v10, 16, v13
	v_and_b32_e32 v11, 0xffff0000, v13
	v_pk_fma_f32 v[6:7], v[6:7], v[8:9], v[10:11]
	v_add_u32_e32 v1, 0x500, v15
	v_cvt_pk_bf16_f32 v5, v6, v7
	v_ashrrev_i32_e32 v1, 4, v1
	global_store_dwordx4 v[16:17], v[2:5], off
	s_and_b64 vcc, exec, s[0:1]
	s_nop 0
	v_add_u32_e32 v2, s69, v1
	v_mov_b64_e32 v[4:5], s[4:5]
	v_mad_i64_i32 v[4:5], s[50:51], v2, s66, v[4:5]
	v_lshl_add_u64 v[4:5], s[16:17], 1, v[4:5]
	v_lshl_add_u64 v[4:5], s[22:23], 1, v[4:5]
	v_lshl_add_u64 v[4:5], v[4:5], 0, v[128:129]
	v_mov_b64_e32 v[8:9], v[40:41]
	v_mov_b64_e32 v[10:11], v[42:43]
	v_mad_u64_u32 v[4:5], s[50:51], v1, s60, v[14:15]
	ds_read_b128 v[4:7], v4
	v_ashrrev_i32_e32 v3, 31, v2
	v_lshlrev_b64 v[2:3], 11, v[2:3]
	v_lshl_add_u64 v[2:3], s[24:25], 0, v[2:3]
	v_lshl_add_u64 v[12:13], v[2:3], 0, v[128:129]
	v_mov_b32_e32 v1, 0
	v_mov_b32_e32 v2, 0
	v_mov_b32_e32 v3, 0
	s_cbranch_vccnz .LBB0_1758
	v_mov_b64_e32 v[0:1], v[68:69]
	v_mov_b64_e32 v[2:3], v[70:71]
.LBB0_1758:
	v_lshlrev_b32_e32 v16, 16, v8
	v_and_b32_e32 v17, 0xffff0000, v8
	s_waitcnt lgkmcnt(0)
	v_lshlrev_b32_e32 v18, 16, v4
	v_and_b32_e32 v19, 0xffff0000, v4
	v_lshlrev_b32_e32 v20, 16, v0
	v_and_b32_e32 v21, 0xffff0000, v0
	v_pk_fma_f32 v[16:17], v[16:17], v[18:19], v[20:21]
	v_lshlrev_b32_e32 v8, 16, v9
	v_cvt_pk_bf16_f32 v0, v16, v17
	v_and_b32_e32 v9, 0xffff0000, v9
	v_lshlrev_b32_e32 v4, 16, v5
	v_and_b32_e32 v5, 0xffff0000, v5
	v_lshlrev_b32_e32 v16, 16, v1
	v_and_b32_e32 v17, 0xffff0000, v1
	v_pk_fma_f32 v[4:5], v[8:9], v[4:5], v[16:17]
	v_lshlrev_b32_e32 v8, 16, v6
	v_cvt_pk_bf16_f32 v1, v4, v5
	v_lshlrev_b32_e32 v4, 16, v10
	v_and_b32_e32 v5, 0xffff0000, v10
	v_and_b32_e32 v9, 0xffff0000, v6
	v_lshlrev_b32_e32 v16, 16, v2
	v_and_b32_e32 v17, 0xffff0000, v2
	v_pk_fma_f32 v[4:5], v[4:5], v[8:9], v[16:17]
	v_lshlrev_b32_e32 v6, 16, v7
	v_cvt_pk_bf16_f32 v2, v4, v5
	v_lshlrev_b32_e32 v4, 16, v11
	v_and_b32_e32 v5, 0xffff0000, v11
	v_and_b32_e32 v7, 0xffff0000, v7
	v_lshlrev_b32_e32 v8, 16, v3
	v_and_b32_e32 v9, 0xffff0000, v3
	v_pk_fma_f32 v[4:5], v[4:5], v[6:7], v[8:9]
	s_and_b64 vcc, exec, s[0:1]
	v_cvt_pk_bf16_f32 v3, v4, v5
	global_store_dwordx4 v[12:13], v[0:3], off
	v_mov_b32_e32 v10, 0
	v_mov_b32_e32 v11, 0
	v_add_u32_e32 v0, 0x600, v15
	v_ashrrev_i32_e32 v1, 4, v0
	v_add_u32_e32 v0, s69, v1
	v_mov_b64_e32 v[2:3], s[4:5]
	v_mad_i64_i32 v[2:3], s[50:51], v0, s66, v[2:3]
	v_lshl_add_u64 v[2:3], s[16:17], 1, v[2:3]
	v_lshl_add_u64 v[2:3], s[22:23], 1, v[2:3]
	v_lshl_add_u64 v[2:3], v[2:3], 0, v[128:129]
	v_mov_b64_e32 v[6:7], v[44:45]
	v_mov_b64_e32 v[8:9], v[46:47]
	v_mad_u64_u32 v[2:3], s[50:51], v1, s60, v[14:15]
	ds_read_b128 v[2:5], v2
	v_ashrrev_i32_e32 v1, 31, v0
	v_lshlrev_b64 v[0:1], 11, v[0:1]
	v_lshl_add_u64 v[0:1], s[24:25], 0, v[0:1]
	v_lshl_add_u64 v[16:17], v[0:1], 0, v[128:129]
	v_mov_b32_e32 v0, 0
	v_mov_b32_e32 v12, 0
	v_mov_b32_e32 v13, 0
	s_cbranch_vccnz .LBB0_1760
	v_mov_b64_e32 v[10:11], v[72:73]
	v_mov_b64_e32 v[12:13], v[74:75]
.LBB0_1760:
	v_lshlrev_b32_e32 v18, 16, v6
	v_and_b32_e32 v19, 0xffff0000, v6
	s_waitcnt lgkmcnt(0)
	v_lshlrev_b32_e32 v20, 16, v2
	v_and_b32_e32 v21, 0xffff0000, v2
	v_lshlrev_b32_e32 v22, 16, v10
	v_and_b32_e32 v23, 0xffff0000, v10
	v_pk_fma_f32 v[18:19], v[18:19], v[20:21], v[22:23]
	v_lshlrev_b32_e32 v6, 16, v7
	v_cvt_pk_bf16_f32 v2, v18, v19
	v_and_b32_e32 v7, 0xffff0000, v7
	v_lshlrev_b32_e32 v18, 16, v3
	v_and_b32_e32 v19, 0xffff0000, v3
	v_lshlrev_b32_e32 v10, 16, v11
	v_and_b32_e32 v11, 0xffff0000, v11
	v_pk_fma_f32 v[6:7], v[6:7], v[18:19], v[10:11]
	v_lshlrev_b32_e32 v10, 16, v4
	v_cvt_pk_bf16_f32 v3, v6, v7
	v_lshlrev_b32_e32 v6, 16, v8
	v_and_b32_e32 v7, 0xffff0000, v8
	v_and_b32_e32 v11, 0xffff0000, v4
	v_lshlrev_b32_e32 v18, 16, v12
	v_and_b32_e32 v19, 0xffff0000, v12
	v_pk_fma_f32 v[6:7], v[6:7], v[10:11], v[18:19]
	v_lshlrev_b32_e32 v8, 16, v5
	v_cvt_pk_bf16_f32 v4, v6, v7
	v_lshlrev_b32_e32 v6, 16, v9
	v_and_b32_e32 v7, 0xffff0000, v9
	v_and_b32_e32 v9, 0xffff0000, v5
	v_lshlrev_b32_e32 v10, 16, v13
	v_and_b32_e32 v11, 0xffff0000, v13
	v_pk_fma_f32 v[6:7], v[6:7], v[8:9], v[10:11]
	v_add_u32_e32 v1, 0x700, v15
	v_cvt_pk_bf16_f32 v5, v6, v7
	v_ashrrev_i32_e32 v1, 4, v1
	global_store_dwordx4 v[16:17], v[2:5], off
	s_and_b64 vcc, exec, s[0:1]
	s_nop 0
	v_add_u32_e32 v2, s69, v1
	v_mov_b64_e32 v[4:5], s[4:5]
	v_mad_i64_i32 v[4:5], s[50:51], v2, s66, v[4:5]
	v_lshl_add_u64 v[4:5], s[16:17], 1, v[4:5]
	v_lshl_add_u64 v[4:5], s[22:23], 1, v[4:5]
	v_lshl_add_u64 v[4:5], v[4:5], 0, v[128:129]
	v_mov_b64_e32 v[8:9], v[48:49]
	v_mov_b64_e32 v[10:11], v[50:51]
	v_mad_u64_u32 v[4:5], s[50:51], v1, s60, v[14:15]
	ds_read_b128 v[4:7], v4
	v_ashrrev_i32_e32 v3, 31, v2
	v_lshlrev_b64 v[2:3], 11, v[2:3]
	v_lshl_add_u64 v[2:3], s[24:25], 0, v[2:3]
	v_lshl_add_u64 v[12:13], v[2:3], 0, v[128:129]
	v_mov_b32_e32 v1, 0
	v_mov_b32_e32 v2, 0
	v_mov_b32_e32 v3, 0
	s_cbranch_vccnz .LBB0_1743
	v_mov_b64_e32 v[0:1], v[76:77]
	v_mov_b64_e32 v[2:3], v[78:79]
	s_branch .LBB0_1743

.LBB0_1820:
	v_lshl_add_u64 v[18:19], v[0:1], 0, s[18:19]
	s_waitcnt lgkmcnt(0)
	global_load_dwordx4 v[26:29], v[18:19], off
	v_add_co_u32_e32 v200, vcc, 0x8000, v18
	s_nop 1
	v_addc_co_u32_e32 v201, vcc, 0, v19, vcc
	global_load_dwordx4 v[208:211], v[200:201], off
	v_add_co_u32_e32 v200, vcc, 0x10000, v18
	s_nop 1
	v_addc_co_u32_e32 v201, vcc, 0, v19, vcc
	global_load_dwordx4 v[212:215], v[200:201], off
	v_add_co_u32_e32 v200, vcc, 0x18000, v18
	s_nop 1
	v_addc_co_u32_e32 v201, vcc, 0, v19, vcc
	global_load_dwordx4 v[216:219], v[200:201], off
	ds_read_b128 v[30:33], v25
	s_waitcnt vmcnt(3) lgkmcnt(0)
	v_pk_fma_f32 v[30:31], v[26:27], s[16:17], v[30:31] op_sel_hi:[1,0,1]
	v_pk_fma_f32 v[32:33], v[28:29], s[16:17], v[32:33] op_sel_hi:[1,0,1]
	v_pk_mul_f32 v[26:27], v[30:31], v[30:31]
	v_add_f32_e32 v34, v30, v31
	v_pk_mul_f32 v[28:29], v[32:33], v[32:33]
	v_add_f32_e32 v26, v26, v27
	v_add_f32_e32 v34, v32, v34
	v_add_f32_e32 v26, v28, v26
	v_add_f32_e32 v27, v33, v34
	v_add_f32_e32 v26, v29, v26
	ds_bpermute_b32 v28, v20, v27
	ds_bpermute_b32 v29, v20, v26
	v_lshl_add_u64 v[34:35], v[14:15], 0, s[18:19]
	v_add_co_u32_e32 v34, vcc, s56, v34
	s_waitcnt lgkmcnt(1)
	v_add_f32_e32 v27, v27, v28
	s_waitcnt lgkmcnt(0)
	v_add_f32_e32 v26, v26, v29
	ds_bpermute_b32 v28, v21, v27
	ds_bpermute_b32 v29, v21, v26
	v_addc_co_u32_e32 v35, vcc, 0, v35, vcc
	global_store_dwordx4 v[34:35], v[30:33], off offset:3584
	s_waitcnt lgkmcnt(1)
	v_add_f32_e32 v27, v27, v28
	s_waitcnt lgkmcnt(0)
	v_add_f32_e32 v26, v26, v29
	ds_bpermute_b32 v28, v22, v27
	ds_bpermute_b32 v29, v22, v26
	s_waitcnt lgkmcnt(1)
	v_add_f32_e32 v27, v27, v28
	s_waitcnt lgkmcnt(0)
	v_add_f32_e32 v28, v26, v29
	ds_bpermute_b32 v26, v23, v27
	ds_bpermute_b32 v29, v23, v28
	s_waitcnt lgkmcnt(1)
	v_add_f32_e32 v26, v27, v26
	s_waitcnt lgkmcnt(0)
	v_add_f32_e32 v27, v28, v29
	ds_bpermute_b32 v28, v24, v26
	ds_bpermute_b32 v29, v24, v27
	s_and_saveexec_b64 s[22:23], s[0:1]
	s_cbranch_execz .LBB0_1822
	s_waitcnt lgkmcnt(0)
	v_add_f32_e32 v29, v27, v29
	v_add_f32_e32 v28, v26, v28
	v_lshl_add_u64 v[26:27], s[20:21], 0, v[16:17]
	v_add_co_u32_e32 v26, vcc, 0x3c000, v26
	s_nop 1
	v_addc_co_u32_e32 v27, vcc, 0, v27, vcc
	v_mov_b32_e32 v92, v26
	v_mov_b32_e32 v93, v27
	v_and_b32_e32 v90, 0x3ff, v26
	v_add_u32_e32 v90, 68608, v90
	ds_write2_b32 v90, v28, v29 offset1:1
.LBB0_1822:
	s_or_b64 exec, exec, s[22:23]
	v_add_co_u32_e32 v26, vcc, 0x8000, v18
	ds_read_b128 v[30:33], v25 offset:4224
	s_nop 0
	v_addc_co_u32_e32 v27, vcc, 0, v19, vcc
	s_waitcnt lgkmcnt(1)
	s_waitcnt vmcnt(3)
	v_mov_b64_e32 v[26:27], v[208:209]
	v_mov_b64_e32 v[28:29], v[210:211]
	s_waitcnt lgkmcnt(0)
	v_pk_fma_f32 v[30:31], v[26:27], s[16:17], v[30:31] op_sel_hi:[1,0,1]
	v_pk_fma_f32 v[32:33], v[28:29], s[16:17], v[32:33] op_sel_hi:[1,0,1]
	v_pk_mul_f32 v[26:27], v[30:31], v[30:31]
	v_add_f32_e32 v34, v30, v31
	v_pk_mul_f32 v[28:29], v[32:33], v[32:33]
	v_add_f32_e32 v26, v26, v27
	v_add_f32_e32 v34, v32, v34
	v_add_f32_e32 v26, v28, v26
	v_add_f32_e32 v27, v33, v34
	v_add_f32_e32 v26, v29, v26
	ds_bpermute_b32 v28, v20, v27
	ds_bpermute_b32 v29, v20, v26
	v_lshl_add_u64 v[34:35], v[12:13], 0, s[18:19]
	v_add_co_u32_e32 v34, vcc, s56, v34
	s_waitcnt lgkmcnt(1)
	v_add_f32_e32 v27, v27, v28
	s_waitcnt lgkmcnt(0)
	v_add_f32_e32 v26, v26, v29
	ds_bpermute_b32 v28, v21, v27
	ds_bpermute_b32 v29, v21, v26
	v_addc_co_u32_e32 v35, vcc, 0, v35, vcc
	global_store_dwordx4 v[34:35], v[30:33], off offset:3584
	s_waitcnt lgkmcnt(1)
	v_add_f32_e32 v27, v27, v28
	s_waitcnt lgkmcnt(0)
	v_add_f32_e32 v26, v26, v29
	ds_bpermute_b32 v28, v22, v27
	ds_bpermute_b32 v29, v22, v26
	s_waitcnt lgkmcnt(1)
	v_add_f32_e32 v27, v27, v28
	s_waitcnt lgkmcnt(0)
	v_add_f32_e32 v28, v26, v29
	ds_bpermute_b32 v26, v23, v27
	ds_bpermute_b32 v29, v23, v28
	s_waitcnt lgkmcnt(1)
	v_add_f32_e32 v26, v27, v26
	s_waitcnt lgkmcnt(0)
	v_add_f32_e32 v27, v28, v29
	ds_bpermute_b32 v28, v24, v26
	ds_bpermute_b32 v29, v24, v27
	s_and_saveexec_b64 s[22:23], s[0:1]
	s_cbranch_execz .LBB0_1824
	s_waitcnt lgkmcnt(0)
	v_add_f32_e32 v29, v27, v29
	v_add_f32_e32 v28, v26, v28
	v_lshl_add_u64 v[26:27], s[20:21], 0, v[10:11]
	v_add_co_u32_e32 v26, vcc, 0x3c000, v26
	s_nop 1
	v_addc_co_u32_e32 v27, vcc, 0, v27, vcc
	v_mov_b32_e32 v92, v26
	v_mov_b32_e32 v93, v27
	v_and_b32_e32 v90, 0x3ff, v26
	v_add_u32_e32 v90, 68608, v90
	ds_write2_b32 v90, v28, v29 offset1:1
.LBB0_1824:
	s_or_b64 exec, exec, s[22:23]
	v_add_co_u32_e32 v26, vcc, 0x10000, v18
	ds_read_b128 v[30:33], v25 offset:8448
	s_nop 0
	v_addc_co_u32_e32 v27, vcc, 0, v19, vcc
	s_waitcnt lgkmcnt(1)
	s_waitcnt vmcnt(3)
	v_mov_b64_e32 v[26:27], v[212:213]
	v_mov_b64_e32 v[28:29], v[214:215]
	s_waitcnt lgkmcnt(0)
	v_pk_fma_f32 v[30:31], v[26:27], s[16:17], v[30:31] op_sel_hi:[1,0,1]
	v_pk_fma_f32 v[32:33], v[28:29], s[16:17], v[32:33] op_sel_hi:[1,0,1]
	v_pk_mul_f32 v[26:27], v[30:31], v[30:31]
	v_add_f32_e32 v34, v30, v31
	v_pk_mul_f32 v[28:29], v[32:33], v[32:33]
	v_add_f32_e32 v26, v26, v27
	v_add_f32_e32 v34, v32, v34
	v_add_f32_e32 v26, v28, v26
	v_add_f32_e32 v27, v33, v34
	v_add_f32_e32 v26, v29, v26
	ds_bpermute_b32 v28, v20, v27
	ds_bpermute_b32 v29, v20, v26
	v_lshl_add_u64 v[34:35], v[8:9], 0, s[18:19]
	v_add_co_u32_e32 v34, vcc, s56, v34
	s_waitcnt lgkmcnt(1)
	v_add_f32_e32 v27, v27, v28
	s_waitcnt lgkmcnt(0)
	v_add_f32_e32 v26, v26, v29
	ds_bpermute_b32 v28, v21, v27
	ds_bpermute_b32 v29, v21, v26
	v_addc_co_u32_e32 v35, vcc, 0, v35, vcc
	global_store_dwordx4 v[34:35], v[30:33], off offset:3584
	s_waitcnt lgkmcnt(1)
	v_add_f32_e32 v27, v27, v28
	s_waitcnt lgkmcnt(0)
	v_add_f32_e32 v26, v26, v29
	ds_bpermute_b32 v28, v22, v27
	ds_bpermute_b32 v29, v22, v26
	s_waitcnt lgkmcnt(1)
	v_add_f32_e32 v27, v27, v28
	s_waitcnt lgkmcnt(0)
	v_add_f32_e32 v28, v26, v29
	ds_bpermute_b32 v26, v23, v27
	ds_bpermute_b32 v29, v23, v28
	s_waitcnt lgkmcnt(1)
	v_add_f32_e32 v26, v27, v26
	s_waitcnt lgkmcnt(0)
	v_add_f32_e32 v27, v28, v29
	ds_bpermute_b32 v28, v24, v26
	ds_bpermute_b32 v29, v24, v27
	s_and_saveexec_b64 s[22:23], s[0:1]
	s_cbranch_execz .LBB0_1826
	s_waitcnt lgkmcnt(0)
	v_add_f32_e32 v29, v27, v29
	v_add_f32_e32 v28, v26, v28
	v_lshl_add_u64 v[26:27], s[20:21], 0, v[6:7]
	v_add_co_u32_e32 v26, vcc, 0x3c000, v26
	s_nop 1
	v_addc_co_u32_e32 v27, vcc, 0, v27, vcc
	v_mov_b32_e32 v92, v26
	v_mov_b32_e32 v93, v27
	v_and_b32_e32 v90, 0x3ff, v26
	v_add_u32_e32 v90, 68608, v90
	ds_write2_b32 v90, v28, v29 offset1:1
.LBB0_1826:
	s_or_b64 exec, exec, s[22:23]
	v_add_co_u32_e32 v18, vcc, 0x18000, v18
	ds_read_b128 v[30:33], v25 offset:12672
	s_nop 0
	v_addc_co_u32_e32 v19, vcc, 0, v19, vcc
	s_waitcnt lgkmcnt(1)
	s_waitcnt vmcnt(3)
	v_mov_b64_e32 v[26:27], v[216:217]
	v_mov_b64_e32 v[28:29], v[218:219]
	s_waitcnt lgkmcnt(0)
	v_pk_fma_f32 v[30:31], v[26:27], s[16:17], v[30:31] op_sel_hi:[1,0,1]
	v_pk_fma_f32 v[32:33], v[28:29], s[16:17], v[32:33] op_sel_hi:[1,0,1]
	v_pk_mul_f32 v[18:19], v[30:31], v[30:31]
	v_add_f32_e32 v28, v30, v31
	v_pk_mul_f32 v[26:27], v[32:33], v[32:33]
	v_add_f32_e32 v18, v18, v19
	v_add_f32_e32 v28, v32, v28
	v_add_f32_e32 v18, v26, v18
	v_add_f32_e32 v19, v33, v28
	v_add_f32_e32 v18, v27, v18
	ds_bpermute_b32 v26, v20, v19
	ds_bpermute_b32 v27, v20, v18
	v_lshl_add_u64 v[28:29], v[4:5], 0, s[18:19]
	v_add_co_u32_e32 v28, vcc, s56, v28
	s_waitcnt lgkmcnt(1)
	v_add_f32_e32 v19, v19, v26
	s_waitcnt lgkmcnt(0)
	v_add_f32_e32 v18, v18, v27
	ds_bpermute_b32 v26, v21, v19
	ds_bpermute_b32 v27, v21, v18
	v_addc_co_u32_e32 v29, vcc, 0, v29, vcc
	global_store_dwordx4 v[28:29], v[30:33], off offset:3584
	s_waitcnt lgkmcnt(1)
	v_add_f32_e32 v19, v19, v26
	s_waitcnt lgkmcnt(0)
	v_add_f32_e32 v18, v18, v27
	ds_bpermute_b32 v26, v22, v19
	ds_bpermute_b32 v27, v22, v18
	s_waitcnt lgkmcnt(1)
	v_add_f32_e32 v19, v19, v26
	s_waitcnt lgkmcnt(0)
	v_add_f32_e32 v26, v18, v27
	ds_bpermute_b32 v18, v23, v19
	ds_bpermute_b32 v27, v23, v26
	s_waitcnt lgkmcnt(1)
	v_add_f32_e32 v18, v19, v18
	s_waitcnt lgkmcnt(0)
	v_add_f32_e32 v19, v26, v27
	ds_bpermute_b32 v26, v24, v18
	ds_bpermute_b32 v27, v24, v19
	s_and_saveexec_b64 s[22:23], s[0:1]
	s_cbranch_execz .LBB0_1819
	s_waitcnt lgkmcnt(0)
	v_add_f32_e32 v27, v19, v27
	v_add_f32_e32 v26, v18, v26
	v_lshl_add_u64 v[18:19], s[20:21], 0, v[2:3]
	v_add_co_u32_e32 v18, vcc, 0x3c000, v18
	s_nop 1
	v_addc_co_u32_e32 v19, vcc, 0, v19, vcc
	v_mov_b32_e32 v92, v18
	v_mov_b32_e32 v93, v19
	v_and_b32_e32 v90, 0x3ff, v18
	v_add_u32_e32 v90, 68608, v90
	ds_write2_b32 v90, v26, v27 offset1:1
	s_branch .LBB0_1819

.LBB0_3732:
	s_add_i32 s26, s26, 1
	s_add_u32 s42, s42, 0x100000
	s_addc_u32 s43, s43, 0
	v_lshlrev_b32_e32 v14, 16, v8
	v_and_b32_e32 v15, 0xffff0000, v8
	s_waitcnt lgkmcnt(0)
	v_lshlrev_b32_e32 v16, 16, v4
	v_and_b32_e32 v17, 0xffff0000, v4
	v_lshlrev_b32_e32 v18, 16, v0
	v_and_b32_e32 v19, 0xffff0000, v0
	s_add_u32 s40, s40, 0x100000
	v_pk_fma_f32 v[14:15], v[14:15], v[16:17], v[18:19]
	s_addc_u32 s41, s41, 0
	v_cvt_pk_bf16_f32 v0, v14, v15
	v_lshlrev_b32_e32 v8, 16, v9
	v_and_b32_e32 v9, 0xffff0000, v9
	v_lshlrev_b32_e32 v4, 16, v5
	v_and_b32_e32 v5, 0xffff0000, v5
	v_lshlrev_b32_e32 v14, 16, v1
	v_and_b32_e32 v15, 0xffff0000, v1
	s_add_u32 s38, s38, 0x100000
	v_pk_fma_f32 v[4:5], v[8:9], v[4:5], v[14:15]
	s_addc_u32 s39, s39, 0
	v_cvt_pk_bf16_f32 v1, v4, v5
	v_lshlrev_b32_e32 v4, 16, v10
	v_and_b32_e32 v5, 0xffff0000, v10
	v_lshlrev_b32_e32 v8, 16, v6
	v_and_b32_e32 v9, 0xffff0000, v6
	v_lshlrev_b32_e32 v14, 16, v2
	v_and_b32_e32 v15, 0xffff0000, v2
	s_add_u32 s36, s36, 0x100000
	v_pk_fma_f32 v[4:5], v[4:5], v[8:9], v[14:15]
	s_addc_u32 s37, s37, 0
	v_cvt_pk_bf16_f32 v2, v4, v5
	v_lshlrev_b32_e32 v4, 16, v11
	v_and_b32_e32 v5, 0xffff0000, v11
	v_lshlrev_b32_e32 v6, 16, v7
	v_and_b32_e32 v7, 0xffff0000, v7
	v_lshlrev_b32_e32 v8, 16, v3
	v_and_b32_e32 v9, 0xffff0000, v3
	s_add_u32 s34, s34, 0x100000
	v_pk_fma_f32 v[4:5], v[4:5], v[6:7], v[8:9]
	s_addc_u32 s35, s35, 0
	v_cvt_pk_bf16_f32 v3, v4, v5
	s_cmp_lg_u32 s26, s62
	global_store_dwordx4 v[12:13], v[0:3], off
	s_cbranch_scc0 .LBB0_3728

.LBB0_3739:
	v_lshlrev_b32_e32 v16, 16, v8
	v_and_b32_e32 v17, 0xffff0000, v8
	s_waitcnt lgkmcnt(0)
	v_lshlrev_b32_e32 v18, 16, v4
	v_and_b32_e32 v19, 0xffff0000, v4
	v_lshlrev_b32_e32 v20, 16, v0
	v_and_b32_e32 v21, 0xffff0000, v0
	v_pk_fma_f32 v[16:17], v[16:17], v[18:19], v[20:21]
	v_lshlrev_b32_e32 v8, 16, v9
	v_cvt_pk_bf16_f32 v0, v16, v17
	v_and_b32_e32 v9, 0xffff0000, v9
	v_lshlrev_b32_e32 v4, 16, v5
	v_and_b32_e32 v5, 0xffff0000, v5
	v_lshlrev_b32_e32 v16, 16, v1
	v_and_b32_e32 v17, 0xffff0000, v1
	v_pk_fma_f32 v[4:5], v[8:9], v[4:5], v[16:17]
	v_lshlrev_b32_e32 v8, 16, v6
	v_cvt_pk_bf16_f32 v1, v4, v5
	v_lshlrev_b32_e32 v4, 16, v10
	v_and_b32_e32 v5, 0xffff0000, v10
	v_and_b32_e32 v9, 0xffff0000, v6
	v_lshlrev_b32_e32 v16, 16, v2
	v_and_b32_e32 v17, 0xffff0000, v2
	v_pk_fma_f32 v[4:5], v[4:5], v[8:9], v[16:17]
	v_lshlrev_b32_e32 v6, 16, v7
	v_cvt_pk_bf16_f32 v2, v4, v5
	v_lshlrev_b32_e32 v4, 16, v11
	v_and_b32_e32 v5, 0xffff0000, v11
	v_and_b32_e32 v7, 0xffff0000, v7
	v_lshlrev_b32_e32 v8, 16, v3
	v_and_b32_e32 v9, 0xffff0000, v3
	v_pk_fma_f32 v[4:5], v[4:5], v[6:7], v[8:9]
	s_and_b64 vcc, exec, s[0:1]
	v_cvt_pk_bf16_f32 v3, v4, v5
	global_store_dwordx4 v[12:13], v[0:3], off
	v_mov_b32_e32 v10, 0
	v_mov_b32_e32 v11, 0
	v_add_u32_e32 v0, 0x200, v15
	v_ashrrev_i32_e32 v1, 4, v0
	v_add_u32_e32 v0, s63, v1
	v_mov_b64_e32 v[2:3], s[4:5]
	v_mad_i64_i32 v[2:3], s[44:45], v0, s60, v[2:3]
	v_lshl_add_u64 v[2:3], s[16:17], 1, v[2:3]
	v_lshl_add_u64 v[2:3], s[22:23], 1, v[2:3]
	v_lshl_add_u64 v[2:3], v[2:3], 0, v[96:97]
	v_mov_b64_e32 v[6:7], v[28:29]
	v_mov_b64_e32 v[8:9], v[30:31]
	v_mad_u64_u32 v[2:3], s[44:45], v1, s54, v[14:15]
	ds_read_b128 v[2:5], v2
	v_ashrrev_i32_e32 v1, 31, v0
	v_lshlrev_b64 v[0:1], 11, v[0:1]
	v_lshl_add_u64 v[0:1], s[24:25], 0, v[0:1]
	v_lshl_add_u64 v[16:17], v[0:1], 0, v[96:97]
	v_mov_b32_e32 v0, 0
	v_mov_b32_e32 v12, 0
	v_mov_b32_e32 v13, 0
	s_cbranch_vccnz .LBB0_3741
	v_mov_b64_e32 v[10:11], v[56:57]
	v_mov_b64_e32 v[12:13], v[58:59]
.LBB0_3741:
	v_lshlrev_b32_e32 v18, 16, v6
	v_and_b32_e32 v19, 0xffff0000, v6
	s_waitcnt lgkmcnt(0)
	v_lshlrev_b32_e32 v20, 16, v2
	v_and_b32_e32 v21, 0xffff0000, v2
	v_lshlrev_b32_e32 v22, 16, v10
	v_and_b32_e32 v23, 0xffff0000, v10
	v_pk_fma_f32 v[18:19], v[18:19], v[20:21], v[22:23]
	v_lshlrev_b32_e32 v6, 16, v7
	v_cvt_pk_bf16_f32 v2, v18, v19
	v_and_b32_e32 v7, 0xffff0000, v7
	v_lshlrev_b32_e32 v18, 16, v3
	v_and_b32_e32 v19, 0xffff0000, v3
	v_lshlrev_b32_e32 v10, 16, v11
	v_and_b32_e32 v11, 0xffff0000, v11
	v_pk_fma_f32 v[6:7], v[6:7], v[18:19], v[10:11]
	v_lshlrev_b32_e32 v10, 16, v4
	v_cvt_pk_bf16_f32 v3, v6, v7
	v_lshlrev_b32_e32 v6, 16, v8
	v_and_b32_e32 v7, 0xffff0000, v8
	v_and_b32_e32 v11, 0xffff0000, v4
	v_lshlrev_b32_e32 v18, 16, v12
	v_and_b32_e32 v19, 0xffff0000, v12
	v_pk_fma_f32 v[6:7], v[6:7], v[10:11], v[18:19]
	v_lshlrev_b32_e32 v8, 16, v5
	v_cvt_pk_bf16_f32 v4, v6, v7
	v_lshlrev_b32_e32 v6, 16, v9
	v_and_b32_e32 v7, 0xffff0000, v9
	v_and_b32_e32 v9, 0xffff0000, v5
	v_lshlrev_b32_e32 v10, 16, v13
	v_and_b32_e32 v11, 0xffff0000, v13
	v_pk_fma_f32 v[6:7], v[6:7], v[8:9], v[10:11]
	v_add_u32_e32 v1, 0x300, v15
	v_cvt_pk_bf16_f32 v5, v6, v7
	v_ashrrev_i32_e32 v1, 4, v1
	global_store_dwordx4 v[16:17], v[2:5], off
	s_and_b64 vcc, exec, s[0:1]
	s_nop 0
	v_add_u32_e32 v2, s63, v1
	v_mov_b64_e32 v[4:5], s[4:5]
	v_mad_i64_i32 v[4:5], s[44:45], v2, s60, v[4:5]
	v_lshl_add_u64 v[4:5], s[16:17], 1, v[4:5]
	v_lshl_add_u64 v[4:5], s[22:23], 1, v[4:5]
	v_lshl_add_u64 v[4:5], v[4:5], 0, v[96:97]
	v_mov_b64_e32 v[8:9], v[32:33]
	v_mov_b64_e32 v[10:11], v[34:35]
	v_mad_u64_u32 v[4:5], s[44:45], v1, s54, v[14:15]
	ds_read_b128 v[4:7], v4
	v_ashrrev_i32_e32 v3, 31, v2
	v_lshlrev_b64 v[2:3], 11, v[2:3]
	v_lshl_add_u64 v[2:3], s[24:25], 0, v[2:3]
	v_lshl_add_u64 v[12:13], v[2:3], 0, v[96:97]
	v_mov_b32_e32 v1, 0
	v_mov_b32_e32 v2, 0
	v_mov_b32_e32 v3, 0
	s_cbranch_vccnz .LBB0_3743
	v_mov_b64_e32 v[0:1], v[60:61]
	v_mov_b64_e32 v[2:3], v[62:63]
.LBB0_3743:
	v_lshlrev_b32_e32 v16, 16, v8
	v_and_b32_e32 v17, 0xffff0000, v8
	s_waitcnt lgkmcnt(0)
	v_lshlrev_b32_e32 v18, 16, v4
	v_and_b32_e32 v19, 0xffff0000, v4
	v_lshlrev_b32_e32 v20, 16, v0
	v_and_b32_e32 v21, 0xffff0000, v0
	v_pk_fma_f32 v[16:17], v[16:17], v[18:19], v[20:21]
	v_lshlrev_b32_e32 v8, 16, v9
	v_cvt_pk_bf16_f32 v0, v16, v17
	v_and_b32_e32 v9, 0xffff0000, v9
	v_lshlrev_b32_e32 v4, 16, v5
	v_and_b32_e32 v5, 0xffff0000, v5
	v_lshlrev_b32_e32 v16, 16, v1
	v_and_b32_e32 v17, 0xffff0000, v1
	v_pk_fma_f32 v[4:5], v[8:9], v[4:5], v[16:17]
	v_lshlrev_b32_e32 v8, 16, v6
	v_cvt_pk_bf16_f32 v1, v4, v5
	v_lshlrev_b32_e32 v4, 16, v10
	v_and_b32_e32 v5, 0xffff0000, v10
	v_and_b32_e32 v9, 0xffff0000, v6
	v_lshlrev_b32_e32 v16, 16, v2
	v_and_b32_e32 v17, 0xffff0000, v2
	v_pk_fma_f32 v[4:5], v[4:5], v[8:9], v[16:17]
	v_lshlrev_b32_e32 v6, 16, v7
	v_cvt_pk_bf16_f32 v2, v4, v5
	v_lshlrev_b32_e32 v4, 16, v11
	v_and_b32_e32 v5, 0xffff0000, v11
	v_and_b32_e32 v7, 0xffff0000, v7
	v_lshlrev_b32_e32 v8, 16, v3
	v_and_b32_e32 v9, 0xffff0000, v3
	v_pk_fma_f32 v[4:5], v[4:5], v[6:7], v[8:9]
	s_and_b64 vcc, exec, s[0:1]
	v_cvt_pk_bf16_f32 v3, v4, v5
	global_store_dwordx4 v[12:13], v[0:3], off
	v_mov_b32_e32 v10, 0
	v_mov_b32_e32 v11, 0
	v_add_u32_e32 v0, 0x400, v15
	v_ashrrev_i32_e32 v1, 4, v0
	v_add_u32_e32 v0, s63, v1
	v_mov_b64_e32 v[2:3], s[4:5]
	v_mad_i64_i32 v[2:3], s[44:45], v0, s60, v[2:3]
	v_lshl_add_u64 v[2:3], s[16:17], 1, v[2:3]
	v_lshl_add_u64 v[2:3], s[22:23], 1, v[2:3]
	v_lshl_add_u64 v[2:3], v[2:3], 0, v[96:97]
	v_mov_b64_e32 v[6:7], v[36:37]
	v_mov_b64_e32 v[8:9], v[38:39]
	v_mad_u64_u32 v[2:3], s[44:45], v1, s54, v[14:15]
	ds_read_b128 v[2:5], v2
	v_ashrrev_i32_e32 v1, 31, v0
	v_lshlrev_b64 v[0:1], 11, v[0:1]
	v_lshl_add_u64 v[0:1], s[24:25], 0, v[0:1]
	v_lshl_add_u64 v[16:17], v[0:1], 0, v[96:97]
	v_mov_b32_e32 v0, 0
	v_mov_b32_e32 v12, 0
	v_mov_b32_e32 v13, 0
	s_cbranch_vccnz .LBB0_3745
	v_mov_b64_e32 v[10:11], v[64:65]
	v_mov_b64_e32 v[12:13], v[66:67]
.LBB0_3745:
	v_lshlrev_b32_e32 v18, 16, v6
	v_and_b32_e32 v19, 0xffff0000, v6
	s_waitcnt lgkmcnt(0)
	v_lshlrev_b32_e32 v20, 16, v2
	v_and_b32_e32 v21, 0xffff0000, v2
	v_lshlrev_b32_e32 v22, 16, v10
	v_and_b32_e32 v23, 0xffff0000, v10
	v_pk_fma_f32 v[18:19], v[18:19], v[20:21], v[22:23]
	v_lshlrev_b32_e32 v6, 16, v7
	v_cvt_pk_bf16_f32 v2, v18, v19
	v_and_b32_e32 v7, 0xffff0000, v7
	v_lshlrev_b32_e32 v18, 16, v3
	v_and_b32_e32 v19, 0xffff0000, v3
	v_lshlrev_b32_e32 v10, 16, v11
	v_and_b32_e32 v11, 0xffff0000, v11
	v_pk_fma_f32 v[6:7], v[6:7], v[18:19], v[10:11]
	v_lshlrev_b32_e32 v10, 16, v4
	v_cvt_pk_bf16_f32 v3, v6, v7
	v_lshlrev_b32_e32 v6, 16, v8
	v_and_b32_e32 v7, 0xffff0000, v8
	v_and_b32_e32 v11, 0xffff0000, v4
	v_lshlrev_b32_e32 v18, 16, v12
	v_and_b32_e32 v19, 0xffff0000, v12
	v_pk_fma_f32 v[6:7], v[6:7], v[10:11], v[18:19]
	v_lshlrev_b32_e32 v8, 16, v5
	v_cvt_pk_bf16_f32 v4, v6, v7
	v_lshlrev_b32_e32 v6, 16, v9
	v_and_b32_e32 v7, 0xffff0000, v9
	v_and_b32_e32 v9, 0xffff0000, v5
	v_lshlrev_b32_e32 v10, 16, v13
	v_and_b32_e32 v11, 0xffff0000, v13
	v_pk_fma_f32 v[6:7], v[6:7], v[8:9], v[10:11]
	v_add_u32_e32 v1, 0x500, v15
	v_cvt_pk_bf16_f32 v5, v6, v7
	v_ashrrev_i32_e32 v1, 4, v1
	global_store_dwordx4 v[16:17], v[2:5], off
	s_and_b64 vcc, exec, s[0:1]
	s_nop 0
	v_add_u32_e32 v2, s63, v1
	v_mov_b64_e32 v[4:5], s[4:5]
	v_mad_i64_i32 v[4:5], s[44:45], v2, s60, v[4:5]
	v_lshl_add_u64 v[4:5], s[16:17], 1, v[4:5]
	v_lshl_add_u64 v[4:5], s[22:23], 1, v[4:5]
	v_lshl_add_u64 v[4:5], v[4:5], 0, v[96:97]
	v_mov_b64_e32 v[8:9], v[40:41]
	v_mov_b64_e32 v[10:11], v[42:43]
	v_mad_u64_u32 v[4:5], s[44:45], v1, s54, v[14:15]
	ds_read_b128 v[4:7], v4
	v_ashrrev_i32_e32 v3, 31, v2
	v_lshlrev_b64 v[2:3], 11, v[2:3]
	v_lshl_add_u64 v[2:3], s[24:25], 0, v[2:3]
	v_lshl_add_u64 v[12:13], v[2:3], 0, v[96:97]
	v_mov_b32_e32 v1, 0
	v_mov_b32_e32 v2, 0
	v_mov_b32_e32 v3, 0
	s_cbranch_vccnz .LBB0_3747
	v_mov_b64_e32 v[0:1], v[68:69]
	v_mov_b64_e32 v[2:3], v[70:71]
.LBB0_3747:
	v_lshlrev_b32_e32 v16, 16, v8
	v_and_b32_e32 v17, 0xffff0000, v8
	s_waitcnt lgkmcnt(0)
	v_lshlrev_b32_e32 v18, 16, v4
	v_and_b32_e32 v19, 0xffff0000, v4
	v_lshlrev_b32_e32 v20, 16, v0
	v_and_b32_e32 v21, 0xffff0000, v0
	v_pk_fma_f32 v[16:17], v[16:17], v[18:19], v[20:21]
	v_lshlrev_b32_e32 v8, 16, v9
	v_cvt_pk_bf16_f32 v0, v16, v17
	v_and_b32_e32 v9, 0xffff0000, v9
	v_lshlrev_b32_e32 v4, 16, v5
	v_and_b32_e32 v5, 0xffff0000, v5
	v_lshlrev_b32_e32 v16, 16, v1
	v_and_b32_e32 v17, 0xffff0000, v1
	v_pk_fma_f32 v[4:5], v[8:9], v[4:5], v[16:17]
	v_lshlrev_b32_e32 v8, 16, v6
	v_cvt_pk_bf16_f32 v1, v4, v5
	v_lshlrev_b32_e32 v4, 16, v10
	v_and_b32_e32 v5, 0xffff0000, v10
	v_and_b32_e32 v9, 0xffff0000, v6
	v_lshlrev_b32_e32 v16, 16, v2
	v_and_b32_e32 v17, 0xffff0000, v2
	v_pk_fma_f32 v[4:5], v[4:5], v[8:9], v[16:17]
	v_lshlrev_b32_e32 v6, 16, v7
	v_cvt_pk_bf16_f32 v2, v4, v5
	v_lshlrev_b32_e32 v4, 16, v11
	v_and_b32_e32 v5, 0xffff0000, v11
	v_and_b32_e32 v7, 0xffff0000, v7
	v_lshlrev_b32_e32 v8, 16, v3
	v_and_b32_e32 v9, 0xffff0000, v3
	v_pk_fma_f32 v[4:5], v[4:5], v[6:7], v[8:9]
	s_and_b64 vcc, exec, s[0:1]
	v_cvt_pk_bf16_f32 v3, v4, v5
	global_store_dwordx4 v[12:13], v[0:3], off
	v_mov_b32_e32 v10, 0
	v_mov_b32_e32 v11, 0
	v_add_u32_e32 v0, 0x600, v15
	v_ashrrev_i32_e32 v1, 4, v0
	v_add_u32_e32 v0, s63, v1
	v_mov_b64_e32 v[2:3], s[4:5]
	v_mad_i64_i32 v[2:3], s[44:45], v0, s60, v[2:3]
	v_lshl_add_u64 v[2:3], s[16:17], 1, v[2:3]
	v_lshl_add_u64 v[2:3], s[22:23], 1, v[2:3]
	v_lshl_add_u64 v[2:3], v[2:3], 0, v[96:97]
	v_mov_b64_e32 v[6:7], v[44:45]
	v_mov_b64_e32 v[8:9], v[46:47]
	v_mad_u64_u32 v[2:3], s[44:45], v1, s54, v[14:15]
	ds_read_b128 v[2:5], v2
	v_ashrrev_i32_e32 v1, 31, v0
	v_lshlrev_b64 v[0:1], 11, v[0:1]
	v_lshl_add_u64 v[0:1], s[24:25], 0, v[0:1]
	v_lshl_add_u64 v[16:17], v[0:1], 0, v[96:97]
	v_mov_b32_e32 v0, 0
	v_mov_b32_e32 v12, 0
	v_mov_b32_e32 v13, 0
	s_cbranch_vccnz .LBB0_3749
	v_mov_b64_e32 v[10:11], v[72:73]
	v_mov_b64_e32 v[12:13], v[74:75]
.LBB0_3749:
	v_lshlrev_b32_e32 v18, 16, v6
	v_and_b32_e32 v19, 0xffff0000, v6
	s_waitcnt lgkmcnt(0)
	v_lshlrev_b32_e32 v20, 16, v2
	v_and_b32_e32 v21, 0xffff0000, v2
	v_lshlrev_b32_e32 v22, 16, v10
	v_and_b32_e32 v23, 0xffff0000, v10
	v_pk_fma_f32 v[18:19], v[18:19], v[20:21], v[22:23]
	v_lshlrev_b32_e32 v6, 16, v7
	v_cvt_pk_bf16_f32 v2, v18, v19
	v_and_b32_e32 v7, 0xffff0000, v7
	v_lshlrev_b32_e32 v18, 16, v3
	v_and_b32_e32 v19, 0xffff0000, v3
	v_lshlrev_b32_e32 v10, 16, v11
	v_and_b32_e32 v11, 0xffff0000, v11
	v_pk_fma_f32 v[6:7], v[6:7], v[18:19], v[10:11]
	v_lshlrev_b32_e32 v10, 16, v4
	v_cvt_pk_bf16_f32 v3, v6, v7
	v_lshlrev_b32_e32 v6, 16, v8
	v_and_b32_e32 v7, 0xffff0000, v8
	v_and_b32_e32 v11, 0xffff0000, v4
	v_lshlrev_b32_e32 v18, 16, v12
	v_and_b32_e32 v19, 0xffff0000, v12
	v_pk_fma_f32 v[6:7], v[6:7], v[10:11], v[18:19]
	v_lshlrev_b32_e32 v8, 16, v5
	v_cvt_pk_bf16_f32 v4, v6, v7
	v_lshlrev_b32_e32 v6, 16, v9
	v_and_b32_e32 v7, 0xffff0000, v9
	v_and_b32_e32 v9, 0xffff0000, v5
	v_lshlrev_b32_e32 v10, 16, v13
	v_and_b32_e32 v11, 0xffff0000, v13
	v_pk_fma_f32 v[6:7], v[6:7], v[8:9], v[10:11]
	v_add_u32_e32 v1, 0x700, v15
	v_cvt_pk_bf16_f32 v5, v6, v7
	v_ashrrev_i32_e32 v1, 4, v1
	global_store_dwordx4 v[16:17], v[2:5], off
	s_and_b64 vcc, exec, s[0:1]
	s_nop 0
	v_add_u32_e32 v2, s63, v1
	v_mov_b64_e32 v[4:5], s[4:5]
	v_mad_i64_i32 v[4:5], s[44:45], v2, s60, v[4:5]
	v_lshl_add_u64 v[4:5], s[16:17], 1, v[4:5]
	v_lshl_add_u64 v[4:5], s[22:23], 1, v[4:5]
	v_lshl_add_u64 v[4:5], v[4:5], 0, v[96:97]
	v_mov_b64_e32 v[8:9], v[48:49]
	v_mov_b64_e32 v[10:11], v[50:51]
	v_mad_u64_u32 v[4:5], s[44:45], v1, s54, v[14:15]
	ds_read_b128 v[4:7], v4
	v_ashrrev_i32_e32 v3, 31, v2
	v_lshlrev_b64 v[2:3], 11, v[2:3]
	v_lshl_add_u64 v[2:3], s[24:25], 0, v[2:3]
	v_lshl_add_u64 v[12:13], v[2:3], 0, v[96:97]
	v_mov_b32_e32 v1, 0
	v_mov_b32_e32 v2, 0
	v_mov_b32_e32 v3, 0
	s_cbranch_vccnz .LBB0_3732
	v_mov_b64_e32 v[0:1], v[76:77]
	v_mov_b64_e32 v[2:3], v[78:79]
	s_branch .LBB0_3732
